# sc1-stores-also-for-EpiBf16X-outputs
# speedup vs baseline: 1.0562x; 1.0048x over previous
.LBB0_440:
	v_add_u32_e32 v98, s8, v247
	v_ashrrev_i32_e32 v99, 31, v98
	v_lshl_add_u64 v[134:135], v[98:99], 1, s[30:31]
	v_mad_u64_u32 v[152:153], s[30:31], v132, s93, 0
	v_mov_b32_e32 v96, v153
	v_mad_u64_u32 v[154:155], s[30:31], v133, s93, v[96:97]
	v_mov_b32_e32 v153, v154
	v_lshl_add_u64 v[152:153], v[152:153], 1, v[134:135]
	v_cvt_pk_bf16_f32 v148, v148, v149
	v_cvt_pk_bf16_f32 v149, v150, v151
	v_cvt_pk_bf16_f32 v151, v136, v137
	v_cvt_pk_bf16_f32 v136, v138, v139
	v_cvt_pk_bf16_f32 v137, v142, v143
	v_cvt_pk_bf16_f32 v138, v146, v147
	v_cvt_pk_bf16_f32 v139, v144, v145
	global_store_dwordx4 v[152:153], v[136:139], off offset:256 sc1
	v_cndmask_b32_e64 v96, 0, 1, s[88:89]
	v_cvt_pk_bf16_f32 v150, v140, v141
	v_or_b32_e32 v136, 16, v132
	v_cmp_ne_u32_e64 s[44:45], 1, v96
	s_andn2_b64 vcc, exec, s[88:89]
	v_ashrrev_i32_e32 v137, 31, v136
	global_store_dwordx4 v[152:153], v[148:151], off sc1
	s_cbranch_vccnz .LBB0_442
	v_lshlrev_b64 v[138:139], 6, v[136:137]
	v_lshl_add_u64 v[138:139], v[206:207], 0, v[138:139]
	s_waitcnt vmcnt(7)
	v_add_f32_e32 v96, v162, v163
	v_add_f32_e32 v133, v164, v165
	v_add_f32_e32 v96, v96, v133
	v_mov_b32_e32 v133, v96
	s_nop 1
	v_permlane16_swap_b32_e32 v96, v133
	v_add_f32_e32 v96, v96, v133
	v_mov_b32_e32 v133, v96
	s_nop 1
	v_permlane32_swap_b32_e32 v96, v133
	v_add_f32_e32 v96, v96, v133
	v_fmamk_f32 v96, v96, 0x3a800000, v225
	v_mul_f32_e32 v133, 0x4b800000, v96
	v_cmp_gt_f32_e32 vcc, s3, v96
	s_nop 1
	v_cndmask_b32_e32 v96, v96, v133, vcc
	v_rsq_f32_e32 v96, v96
	s_nop 0
	v_mul_f32_e32 v133, 0x45800000, v96
	v_cndmask_b32_e32 v96, v96, v133, vcc
	s_branch .LBB0_443

.LBB0_447:
	v_mad_u64_u32 v[138:139], s[30:31], v136, s93, 0
	v_mov_b32_e32 v96, v139
	v_mad_u64_u32 v[136:137], s[30:31], v137, s93, v[96:97]
	v_mov_b32_e32 v139, v136
	v_cvt_pk_bf16_f32 v120, v120, v121
	v_cvt_pk_bf16_f32 v121, v122, v123
	v_cvt_pk_bf16_f32 v122, v116, v117
	v_or_b32_e32 v116, 32, v132
	v_lshl_add_u64 v[136:137], v[138:139], 1, v[134:135]
	v_cvt_pk_bf16_f32 v128, v128, v129
	v_cvt_pk_bf16_f32 v129, v130, v131
	v_cvt_pk_bf16_f32 v130, v124, v125
	v_cvt_pk_bf16_f32 v131, v126, v127
	v_cvt_pk_bf16_f32 v123, v118, v119
	s_and_b64 vcc, exec, s[44:45]
	v_ashrrev_i32_e32 v117, 31, v116
	global_store_dwordx4 v[136:137], v[128:131], off sc1
	global_store_dwordx4 v[136:137], v[120:123], off offset:256 sc1
	s_cbranch_vccnz .LBB0_449
	v_lshlrev_b64 v[118:119], 6, v[116:117]
	v_lshl_add_u64 v[118:119], v[206:207], 0, v[118:119]
	s_waitcnt vmcnt(7)
	v_add_f32_e32 v96, v166, v167
	v_add_f32_e32 v118, v168, v169
	v_add_f32_e32 v96, v96, v118
	v_mov_b32_e32 v118, v96
	s_nop 1
	v_permlane16_swap_b32_e32 v96, v118
	v_add_f32_e32 v96, v96, v118
	v_mov_b32_e32 v118, v96
	s_nop 1
	v_permlane32_swap_b32_e32 v96, v118
	v_add_f32_e32 v96, v96, v118
	v_fmamk_f32 v96, v96, 0x3a800000, v225
	v_mul_f32_e32 v118, 0x4b800000, v96
	v_cmp_gt_f32_e32 vcc, s3, v96
	s_nop 1
	v_cndmask_b32_e32 v96, v96, v118, vcc
	v_rsq_f32_e32 v96, v96
	s_nop 0
	v_mul_f32_e32 v118, 0x45800000, v96
	v_cndmask_b32_e32 v96, v96, v118, vcc
	s_branch .LBB0_450

.LBB0_454:
	v_mad_u64_u32 v[118:119], s[30:31], v116, s93, 0
	v_mov_b32_e32 v96, v119
	v_mad_u64_u32 v[116:117], s[30:31], v117, s93, v[96:97]
	v_mov_b32_e32 v119, v116
	v_cvt_pk_bf16_f32 v104, v104, v105
	v_cvt_pk_bf16_f32 v105, v106, v107
	v_cvt_pk_bf16_f32 v106, v100, v101
	v_or_b32_e32 v100, 48, v132
	v_lshl_add_u64 v[116:117], v[118:119], 1, v[134:135]
	v_cvt_pk_bf16_f32 v112, v112, v113
	v_cvt_pk_bf16_f32 v113, v114, v115
	v_cvt_pk_bf16_f32 v114, v108, v109
	v_cvt_pk_bf16_f32 v115, v110, v111
	v_cvt_pk_bf16_f32 v107, v102, v103
	s_and_b64 vcc, exec, s[44:45]
	v_ashrrev_i32_e32 v101, 31, v100
	global_store_dwordx4 v[116:117], v[112:115], off sc1
	global_store_dwordx4 v[116:117], v[104:107], off offset:256 sc1
	s_cbranch_vccnz .LBB0_456
	v_lshlrev_b64 v[102:103], 6, v[100:101]
	v_lshl_add_u64 v[102:103], v[206:207], 0, v[102:103]
	s_waitcnt vmcnt(7)
	v_add_f32_e32 v96, v170, v171
	v_add_f32_e32 v102, v172, v173
	v_add_f32_e32 v96, v96, v102
	v_mov_b32_e32 v102, v96
	s_nop 1
	v_permlane16_swap_b32_e32 v96, v102
	v_add_f32_e32 v96, v96, v102
	v_mov_b32_e32 v102, v96
	s_nop 1
	v_permlane32_swap_b32_e32 v96, v102
	v_add_f32_e32 v96, v96, v102
	v_fmamk_f32 v96, v96, 0x3a800000, v225
	v_mul_f32_e32 v102, 0x4b800000, v96
	v_cmp_gt_f32_e32 vcc, s3, v96
	s_nop 1
	v_cndmask_b32_e32 v96, v96, v102, vcc
	v_rsq_f32_e32 v96, v96
	s_nop 0
	v_mul_f32_e32 v102, 0x45800000, v96
	v_cndmask_b32_e32 v96, v96, v102, vcc
	s_branch .LBB0_457

.LBB0_461:
	v_mad_u64_u32 v[102:103], s[30:31], v100, s93, 0
	v_mov_b32_e32 v96, v103
	v_mad_u64_u32 v[100:101], s[30:31], v101, s93, v[96:97]
	v_mov_b32_e32 v103, v100
	v_cvt_pk_bf16_f32 v84, v84, v85
	v_cvt_pk_bf16_f32 v85, v86, v87
	v_cvt_pk_bf16_f32 v86, v80, v81
	v_add_u32_e32 v80, 0x80, v132
	v_lshl_add_u64 v[100:101], v[102:103], 1, v[134:135]
	v_cvt_pk_bf16_f32 v92, v92, v93
	v_cvt_pk_bf16_f32 v93, v94, v95
	v_cvt_pk_bf16_f32 v94, v88, v89
	v_cvt_pk_bf16_f32 v95, v90, v91
	v_cvt_pk_bf16_f32 v87, v82, v83
	s_and_b64 vcc, exec, s[44:45]
	v_ashrrev_i32_e32 v81, 31, v80
	global_store_dwordx4 v[100:101], v[92:95], off sc1
	global_store_dwordx4 v[100:101], v[84:87], off offset:256 sc1
	s_cbranch_vccnz .LBB0_463
	v_lshlrev_b64 v[82:83], 6, v[80:81]
	v_lshl_add_u64 v[82:83], v[206:207], 0, v[82:83]
	s_waitcnt vmcnt(7)
	v_add_f32_e32 v82, v174, v175
	v_add_f32_e32 v83, v176, v177
	v_add_f32_e32 v82, v82, v83
	v_mov_b32_e32 v83, v82
	s_nop 1
	v_permlane16_swap_b32_e32 v82, v83
	v_add_f32_e32 v82, v82, v83
	v_mov_b32_e32 v83, v82
	s_nop 1
	v_permlane32_swap_b32_e32 v82, v83
	v_add_f32_e32 v82, v82, v83
	v_fmamk_f32 v82, v82, 0x3a800000, v225
	v_mul_f32_e32 v83, 0x4b800000, v82
	v_cmp_gt_f32_e32 vcc, s3, v82
	s_nop 1
	v_cndmask_b32_e32 v82, v82, v83, vcc
	v_rsq_f32_e32 v82, v82
	s_nop 0
	v_mul_f32_e32 v83, 0x45800000, v82
	v_cndmask_b32_e32 v86, v82, v83, vcc
	s_branch .LBB0_464

.LBB0_468:
	v_mad_u64_u32 v[72:73], s[30:31], v80, s93, 0
	v_mov_b32_e32 v78, v73
	v_mad_u64_u32 v[78:79], s[30:31], v81, s93, v[78:79]
	v_mov_b32_e32 v73, v78
	v_lshl_add_u64 v[72:73], v[72:73], 1, v[134:135]
	v_cvt_pk_bf16_f32 v81, v64, v65
	v_cvt_pk_bf16_f32 v64, v66, v67
	v_cvt_pk_bf16_f32 v65, v74, v75
	v_cvt_pk_bf16_f32 v66, v68, v69
	v_cvt_pk_bf16_f32 v67, v70, v71
	global_store_dwordx4 v[72:73], v[64:67], off offset:256 sc1
	v_cvt_pk_bf16_f32 v78, v82, v83
	v_cvt_pk_bf16_f32 v79, v84, v85
	v_add_u32_e32 v64, 0x90, v132
	v_cvt_pk_bf16_f32 v80, v76, v77
	s_and_b64 vcc, exec, s[44:45]
	v_ashrrev_i32_e32 v65, 31, v64
	global_store_dwordx4 v[72:73], v[78:81], off sc1
	s_cbranch_vccnz .LBB0_470
	v_lshlrev_b64 v[66:67], 6, v[64:65]
	v_lshl_add_u64 v[66:67], v[206:207], 0, v[66:67]
	s_waitcnt vmcnt(7)
	v_add_f32_e32 v66, v178, v179
	v_add_f32_e32 v67, v180, v181
	v_add_f32_e32 v66, v66, v67
	v_mov_b32_e32 v67, v66
	s_nop 1
	v_permlane16_swap_b32_e32 v66, v67
	v_add_f32_e32 v66, v66, v67
	v_mov_b32_e32 v67, v66
	s_nop 1
	v_permlane32_swap_b32_e32 v66, v67
	v_add_f32_e32 v66, v66, v67
	v_fmamk_f32 v66, v66, 0x3a800000, v225
	v_mul_f32_e32 v67, 0x4b800000, v66
	v_cmp_gt_f32_e32 vcc, s3, v66
	s_nop 1
	v_cndmask_b32_e32 v66, v66, v67, vcc
	v_rsq_f32_e32 v66, v66
	s_nop 0
	v_mul_f32_e32 v67, 0x45800000, v66
	v_cndmask_b32_e32 v66, v66, v67, vcc
	s_branch .LBB0_471

.LBB0_475:
	v_mad_u64_u32 v[66:67], s[30:31], v64, s93, 0
	v_mov_b32_e32 v64, v67
	v_mad_u64_u32 v[64:65], s[30:31], v65, s93, v[64:65]
	v_mov_b32_e32 v67, v64
	v_cvt_pk_bf16_f32 v44, v44, v45
	v_cvt_pk_bf16_f32 v45, v46, v47
	v_cvt_pk_bf16_f32 v46, v40, v41
	v_add_u32_e32 v40, 0xa0, v132
	v_lshl_add_u64 v[64:65], v[66:67], 1, v[134:135]
	v_cvt_pk_bf16_f32 v56, v56, v57
	v_cvt_pk_bf16_f32 v57, v58, v59
	v_cvt_pk_bf16_f32 v58, v52, v53
	v_cvt_pk_bf16_f32 v59, v54, v55
	v_cvt_pk_bf16_f32 v47, v42, v43
	s_and_b64 vcc, exec, s[44:45]
	v_ashrrev_i32_e32 v41, 31, v40
	global_store_dwordx4 v[64:65], v[56:59], off sc1
	global_store_dwordx4 v[64:65], v[44:47], off offset:256 sc1
	s_cbranch_vccnz .LBB0_477
	v_lshlrev_b64 v[42:43], 6, v[40:41]
	v_lshl_add_u64 v[42:43], v[206:207], 0, v[42:43]
	s_waitcnt vmcnt(7)
	v_add_f32_e32 v42, v182, v183
	v_add_f32_e32 v43, v184, v185
	v_add_f32_e32 v42, v42, v43
	v_mov_b32_e32 v43, v42
	s_nop 1
	v_permlane16_swap_b32_e32 v42, v43
	v_add_f32_e32 v42, v42, v43
	v_mov_b32_e32 v43, v42
	s_nop 1
	v_permlane32_swap_b32_e32 v42, v43
	v_add_f32_e32 v42, v42, v43
	v_fmamk_f32 v42, v42, 0x3a800000, v225
	v_mul_f32_e32 v43, 0x4b800000, v42
	v_cmp_gt_f32_e32 vcc, s3, v42
	s_nop 1
	v_cndmask_b32_e32 v42, v42, v43, vcc
	v_rsq_f32_e32 v42, v42
	s_nop 0
	v_mul_f32_e32 v43, 0x45800000, v42
	v_cndmask_b32_e32 v42, v42, v43, vcc
	s_branch .LBB0_478

.LBB0_482:
	v_mad_u64_u32 v[42:43], s[30:31], v40, s93, 0
	v_mov_b32_e32 v40, v43
	v_mad_u64_u32 v[40:41], s[30:31], v41, s93, v[40:41]
	v_mov_b32_e32 v43, v40
	v_cvt_pk_bf16_f32 v20, v20, v21
	v_cvt_pk_bf16_f32 v21, v22, v23
	v_cvt_pk_bf16_f32 v22, v16, v17
	v_add_u32_e32 v16, 0xb0, v132
	v_lshl_add_u64 v[40:41], v[42:43], 1, v[134:135]
	v_cvt_pk_bf16_f32 v28, v28, v29
	v_cvt_pk_bf16_f32 v29, v30, v31
	v_cvt_pk_bf16_f32 v30, v24, v25
	v_cvt_pk_bf16_f32 v31, v26, v27
	v_cvt_pk_bf16_f32 v23, v18, v19
	s_and_b64 vcc, exec, s[44:45]
	v_ashrrev_i32_e32 v17, 31, v16
	global_store_dwordx4 v[40:41], v[28:31], off sc1
	global_store_dwordx4 v[40:41], v[20:23], off offset:256 sc1
	s_cbranch_vccnz .LBB0_484
	v_lshlrev_b64 v[18:19], 6, v[16:17]
	v_lshl_add_u64 v[18:19], v[206:207], 0, v[18:19]
	s_waitcnt vmcnt(7)
	v_add_f32_e32 v18, v186, v187
	v_add_f32_e32 v19, v188, v189
	v_add_f32_e32 v18, v18, v19
	v_mov_b32_e32 v19, v18
	s_nop 1
	v_permlane16_swap_b32_e32 v18, v19
	v_add_f32_e32 v18, v18, v19
	v_mov_b32_e32 v19, v18
	s_nop 1
	v_permlane32_swap_b32_e32 v18, v19
	v_add_f32_e32 v18, v18, v19
	v_fmamk_f32 v18, v18, 0x3a800000, v225
	v_mul_f32_e32 v19, 0x4b800000, v18
	v_cmp_gt_f32_e32 vcc, s3, v18
	s_nop 1
	v_cndmask_b32_e32 v18, v18, v19, vcc
	v_rsq_f32_e32 v18, v18
	s_nop 0
	v_mul_f32_e32 v19, 0x45800000, v18
	v_cndmask_b32_e32 v18, v18, v19, vcc
	s_branch .LBB0_485

.LBB0_489:
	v_mad_u64_u32 v[18:19], s[30:31], v16, s93, 0
	v_mov_b32_e32 v16, v19
	v_mad_u64_u32 v[16:17], s[30:31], v17, s93, v[16:17]
	v_mov_b32_e32 v19, v16
	v_lshl_add_u64 v[16:17], v[18:19], 1, v[134:135]
	v_cvt_pk_bf16_f32 v12, v12, v13
	v_cvt_pk_bf16_f32 v13, v14, v15
	v_cvt_pk_bf16_f32 v14, v8, v9
	v_cvt_pk_bf16_f32 v15, v10, v11
	v_cvt_pk_bf16_f32 v4, v4, v5
	v_cvt_pk_bf16_f32 v5, v6, v7
	v_cvt_pk_bf16_f32 v6, v0, v1
	v_cvt_pk_bf16_f32 v7, v2, v3
	s_and_b64 vcc, exec, s[98:99]
	v_readlane_b32 s98, v250, 19
	global_store_dwordx4 v[16:17], v[12:15], off sc1
	global_store_dwordx4 v[16:17], v[4:7], off offset:256 sc1
	v_readlane_b32 s99, v250, 20
	s_cbranch_vccz .LBB0_493
	v_cmp_lt_i32_e32 vcc, v229, v228
	s_nop 1
	v_cndmask_b32_e32 v0, v227, v229, vcc
	v_lshlrev_b32_e32 v27, 2, v0
	ds_bpermute_b32 v0, v27, v60
	ds_bpermute_b32 v1, v27, v61
	ds_bpermute_b32 v4, v27, v62
	ds_bpermute_b32 v5, v27, v63
	ds_bpermute_b32 v8, v27, v48
	ds_bpermute_b32 v9, v27, v49
	ds_bpermute_b32 v12, v27, v50
	ds_bpermute_b32 v13, v27, v51
	ds_bpermute_b32 v16, v27, v36
	ds_bpermute_b32 v17, v27, v37
	ds_bpermute_b32 v20, v27, v38
	ds_bpermute_b32 v21, v27, v39
	ds_bpermute_b32 v24, v27, v32
	ds_bpermute_b32 v25, v27, v33
	ds_bpermute_b32 v26, v27, v34
	ds_bpermute_b32 v27, v27, v35
	v_cmp_lt_i32_e32 vcc, v230, v228
	s_waitcnt lgkmcnt(0)
	v_pk_add_f32 v[0:1], v[60:61], v[0:1]
	v_pk_add_f32 v[4:5], v[62:63], v[4:5]
	v_cndmask_b32_e32 v2, v227, v230, vcc
	v_cmp_lt_i32_e32 vcc, v231, v228
	v_lshlrev_b32_e32 v31, 2, v2
	v_pk_add_f32 v[8:9], v[48:49], v[8:9]
	v_cndmask_b32_e32 v2, v227, v231, vcc
	v_cmp_lt_i32_e32 vcc, v232, v228
	v_pk_add_f32 v[12:13], v[50:51], v[12:13]
	v_pk_add_f32 v[16:17], v[36:37], v[16:17]
	v_cndmask_b32_e32 v6, v227, v232, vcc
	v_pk_add_f32 v[20:21], v[38:39], v[20:21]
	v_pk_add_f32 v[24:25], v[32:33], v[24:25]
	v_pk_add_f32 v[26:27], v[34:35], v[26:27]
	v_lshlrev_b32_e32 v40, 2, v2
	ds_bpermute_b32 v2, v31, v0
	ds_bpermute_b32 v3, v31, v1
	v_lshlrev_b32_e32 v41, 2, v6
	ds_bpermute_b32 v6, v31, v4
	ds_bpermute_b32 v7, v31, v5
	ds_bpermute_b32 v10, v31, v8
	ds_bpermute_b32 v11, v31, v9
	ds_bpermute_b32 v14, v31, v12
	ds_bpermute_b32 v15, v31, v13
	ds_bpermute_b32 v18, v31, v16
	ds_bpermute_b32 v19, v31, v17
	ds_bpermute_b32 v22, v31, v20
	ds_bpermute_b32 v23, v31, v21
	ds_bpermute_b32 v28, v31, v24
	ds_bpermute_b32 v29, v31, v25
	ds_bpermute_b32 v30, v31, v26
	ds_bpermute_b32 v31, v31, v27
	s_waitcnt lgkmcnt(0)
	v_pk_add_f32 v[0:1], v[0:1], v[2:3]
	v_pk_add_f32 v[4:5], v[4:5], v[6:7]
	v_pk_add_f32 v[8:9], v[8:9], v[10:11]
	v_pk_add_f32 v[12:13], v[12:13], v[14:15]
	v_pk_add_f32 v[16:17], v[16:17], v[18:19]
	v_pk_add_f32 v[20:21], v[20:21], v[22:23]
	v_pk_add_f32 v[24:25], v[24:25], v[28:29]
	v_pk_add_f32 v[30:31], v[26:27], v[30:31]
	ds_bpermute_b32 v2, v40, v0
	ds_bpermute_b32 v3, v40, v1
	ds_bpermute_b32 v6, v40, v4
	ds_bpermute_b32 v7, v40, v5
	ds_bpermute_b32 v10, v40, v8
	ds_bpermute_b32 v11, v40, v9
	ds_bpermute_b32 v14, v40, v12
	ds_bpermute_b32 v15, v40, v13
	ds_bpermute_b32 v18, v40, v16
	ds_bpermute_b32 v19, v40, v17
	ds_bpermute_b32 v22, v40, v20
	ds_bpermute_b32 v23, v40, v21
	ds_bpermute_b32 v28, v40, v24
	ds_bpermute_b32 v29, v40, v25
	ds_bpermute_b32 v32, v40, v30
	ds_bpermute_b32 v33, v40, v31
	s_waitcnt lgkmcnt(0)
	v_pk_add_f32 v[0:1], v[0:1], v[2:3]
	v_pk_add_f32 v[4:5], v[4:5], v[6:7]
	v_pk_add_f32 v[8:9], v[8:9], v[10:11]
	v_pk_add_f32 v[12:13], v[12:13], v[14:15]
	v_pk_add_f32 v[16:17], v[16:17], v[18:19]
	v_pk_add_f32 v[20:21], v[20:21], v[22:23]
	v_pk_add_f32 v[24:25], v[24:25], v[28:29]
	v_pk_add_f32 v[28:29], v[30:31], v[32:33]
	ds_bpermute_b32 v2, v41, v0
	ds_bpermute_b32 v3, v41, v1
	ds_bpermute_b32 v6, v41, v4
	ds_bpermute_b32 v7, v41, v5
	ds_bpermute_b32 v10, v41, v8
	ds_bpermute_b32 v11, v41, v9
	ds_bpermute_b32 v14, v41, v12
	ds_bpermute_b32 v15, v41, v13
	ds_bpermute_b32 v18, v41, v16
	ds_bpermute_b32 v19, v41, v17
	ds_bpermute_b32 v22, v41, v20
	ds_bpermute_b32 v23, v41, v21
	ds_bpermute_b32 v26, v41, v24
	ds_bpermute_b32 v27, v41, v25
	ds_bpermute_b32 v30, v41, v28
	ds_bpermute_b32 v31, v41, v29
	s_mov_b64 s[30:31], exec
	v_readlane_b32 s42, v250, 35
	v_readlane_b32 s43, v250, 36
	s_and_b64 s[42:43], s[30:31], s[42:43]
	s_mov_b64 exec, s[42:43]
	s_cbranch_execz .LBB0_492
	s_ashr_i32 s29, s28, 31
	s_lshl_b64 s[28:29], s[28:29], 13
	s_add_u32 s28, s6, s28
	s_addc_u32 s29, s7, s29
	s_waitcnt lgkmcnt(0)
	v_pk_add_f32 v[4:5], v[4:5], v[6:7]
	v_pk_add_f32 v[2:3], v[0:1], v[2:3]
	v_lshl_add_u64 v[0:1], v[98:99], 2, s[28:29]
	v_pk_add_f32 v[28:29], v[28:29], v[30:31]
	v_pk_add_f32 v[26:27], v[24:25], v[26:27]
	v_pk_add_f32 v[20:21], v[20:21], v[22:23]
	v_pk_add_f32 v[18:19], v[16:17], v[18:19]
	v_pk_add_f32 v[12:13], v[12:13], v[14:15]
	v_pk_add_f32 v[10:11], v[8:9], v[10:11]
	global_store_dwordx4 v[0:1], v[2:5], off sc1
	global_store_dwordx4 v[0:1], v[10:13], off offset:16 sc1
	global_store_dwordx4 v[0:1], v[18:21], off offset:512 sc1
	global_store_dwordx4 v[0:1], v[26:29], off offset:528 sc1
